# four down-GEMM phases walk tiles in reverse order (most recently written act rows first)
# baseline (speedup 1.0000x reference)
; __device__ __forceinline__ int opq_tid() { int t = threadIdx.x; asm volatile("" : "+v"(t)); return t; }
; __device__ __forceinline__ int opq_bid() { int b = blockIdx.x; asm volatile("" : "+s"(b)); return b; }
; #define SK_LOAD(AR, BR, k0) do { _Pragma("unroll") for (int i = 0; i < UNR; ++i) { AR[i] = *(const bf16x8*)(ap + (k0) + 32 * i); \
;             _Pragma("unroll") for (int g = 0; g < NG; ++g) BR[g][i] = *(const bf16x8*)(bp[g] + (k0) + 32 * i); } } while (0)
; #define SK_MMA(AR, BR) do { _Pragma("unroll") for (int i = 0; i < UNR; ++i) _Pragma("unroll") for (int g = 0; g < NG; ++g) acc[g] = __builtin_amdgcn_mfma_f32_16x16x32_bf16(BR[g][i], AR[i], acc[g], 0, 0, 0); } while (0)
;     const int tid = opq_tid(), lane = tid & 63, w = tid >> 6, rr = lane & 15, kq = lane >> 4;
;     const int rg = KS == 2 ? (w & 3) : w, kh = KS == 2 ? (w >> 2) : 0, KL = K / KS;
;     for (int u = (opq_bid() + (int)gridDim.x - bshift) % (int)gridDim.x; u < 2 * KS * ngroups; u += gridDim.x) {
;         const int hv = u & (2 * KS - 1), cg = u / (2 * KS), srow = hv * (128 / KS) + rg * 16 + rr;
;         const bf16_t* ap = A + (size_t)srow * K + kh * KL + 8 * kq;
;         const bf16_t* bp[NG]; f32x4 acc[NG];
; #pragma unroll
;         for (int g = 0; g < NG; ++g) { bp[g] = Bt + (size_t)(Epi::brow(cg, g) + rr) * K + kh * KL + 8 * kq; acc[g] = (f32x4){0.f, 0.f, 0.f, 0.f}; }
;         bf16x8 a0[UNR], a1[UNR], b0[NG][UNR], b1[NG][UNR];
;     ...
;         SK_LOAD(a0, b0, 0);
;         for (int k = 0; k < KL; k += 64 * UNR) {
;             SK_LOAD(a1, b1, k + 32 * UNR);
;             SK_MMA(a0, b0);
;             if (k + 64 * UNR < KL) SK_LOAD(a0, b0, k + 64 * UNR);
;             SK_MMA(a1, b1);
;         }
.LBB0_1382:
	s_ashr_i32 s0, s16, 31
	s_lshr_b32 s0, s0, 30
	s_add_i32 s0, s16, s0
	s_ashr_i32 s0, s0, 2
	s_lshl_b32 s12, s0, 4
	v_or_b32_e32 v0, s12, v12
	v_mad_i64_i32 v[94:95], s[14:15], v0, s20, v[8:9]
	global_load_dwordx4 v[0:3], v[94:95], off
	s_and_b32 s1, s17, 0xc0
	v_or_b32_e32 v20, s1, v15
	v_mul_u32_u24_e32 v4, 0xb00, v20
	v_lshlrev_b32_e32 v4, 1, v4
	s_waitcnt vmcnt(4)
	v_lshl_add_u64 v[96:97], v[6:7], 0, v[4:5]
	global_load_dwordx4 v[22:25], v[94:95], off offset:64
	global_load_dwordx4 v[26:29], v[96:97], off
	global_load_dwordx4 v[30:33], v[96:97], off offset:64
	global_load_dwordx4 v[34:37], v[94:95], off offset:128
	global_load_dwordx4 v[38:41], v[94:95], off offset:192
	global_load_dwordx4 v[42:45], v[96:97], off offset:128
	global_load_dwordx4 v[46:49], v[96:97], off offset:192
	global_load_dwordx4 v[50:53], v[94:95], off offset:256
	global_load_dwordx4 v[54:57], v[94:95], off offset:320
	global_load_dwordx4 v[58:61], v[96:97], off offset:256
	global_load_dwordx4 v[62:65], v[96:97], off offset:320
	global_load_dwordx4 v[66:69], v[94:95], off offset:384
	global_load_dwordx4 v[70:73], v[94:95], off offset:448
	global_load_dwordx4 v[74:77], v[96:97], off offset:384
	global_load_dwordx4 v[78:81], v[96:97], off offset:448
	global_load_dwordx4 v[82:85], v[94:95], off offset:512
	global_load_dwordx4 v[86:89], v[94:95], off offset:576
	s_waitcnt vmcnt(15)
	v_mfma_f32_16x16x32_bf16 v[0:3], v[0:3], v[26:29], 0
	global_load_dwordx4 v[26:29], v[96:97], off offset:512
	global_load_dwordx4 v[90:93], v[96:97], off offset:576
	s_waitcnt vmcnt(16)
	v_mfma_f32_16x16x32_bf16 v[0:3], v[22:25], v[30:33], v[0:3]
	global_load_dwordx4 v[22:25], v[94:95], off offset:640
	global_load_dwordx4 v[30:33], v[94:95], off offset:704
	s_waitcnt vmcnt(15)
	v_mfma_f32_16x16x32_bf16 v[0:3], v[34:37], v[42:45], v[0:3]
	global_load_dwordx4 v[34:37], v[96:97], off offset:640
	global_load_dwordx4 v[42:45], v[96:97], off offset:704
	s_waitcnt vmcnt(16)
	v_mfma_f32_16x16x32_bf16 v[0:3], v[38:41], v[46:49], v[0:3]
	global_load_dwordx4 v[38:41], v[94:95], off offset:768
	global_load_dwordx4 v[46:49], v[94:95], off offset:832
	s_waitcnt vmcnt(15)
	v_mfma_f32_16x16x32_bf16 v[0:3], v[50:53], v[58:61], v[0:3]
	global_load_dwordx4 v[50:53], v[96:97], off offset:768
	global_load_dwordx4 v[58:61], v[96:97], off offset:832
	s_waitcnt vmcnt(16)
	v_mfma_f32_16x16x32_bf16 v[0:3], v[54:57], v[62:65], v[0:3]
	global_load_dwordx4 v[54:57], v[94:95], off offset:896
	global_load_dwordx4 v[62:65], v[96:97], off offset:896
	s_waitcnt vmcnt(15)
	v_mfma_f32_16x16x32_bf16 v[0:3], v[66:69], v[74:77], v[0:3]
	global_load_dwordx4 v[66:69], v[94:95], off offset:960
	s_waitcnt vmcnt(15)
	v_mfma_f32_16x16x32_bf16 v[0:3], v[70:73], v[78:81], v[0:3]
	global_load_dwordx4 v[70:73], v[96:97], off offset:960
	s_waitcnt vmcnt(13)
	v_mfma_f32_16x16x32_bf16 v[0:3], v[82:85], v[26:29], v[0:3]
	global_load_dwordx4 v[26:29], v[94:95], off offset:1024
	global_load_dwordx4 v[74:77], v[94:95], off offset:1088
	global_load_dwordx4 v[78:81], v[96:97], off offset:1024
	global_load_dwordx4 v[82:85], v[96:97], off offset:1088
	s_waitcnt vmcnt(16)
	v_mfma_f32_16x16x32_bf16 v[0:3], v[86:89], v[90:93], v[0:3]
	s_waitcnt vmcnt(13)
	v_mfma_f32_16x16x32_bf16 v[0:3], v[22:25], v[34:37], v[0:3]
	global_load_dwordx4 v[22:25], v[94:95], off offset:1152
	global_load_dwordx4 v[34:37], v[94:95], off offset:1216
	s_waitcnt vmcnt(14)
	v_mfma_f32_16x16x32_bf16 v[0:3], v[30:33], v[42:45], v[0:3]
	global_load_dwordx4 v[30:33], v[96:97], off offset:1152
	global_load_dwordx4 v[42:45], v[96:97], off offset:1216
	s_waitcnt vmcnt(13)
	v_mfma_f32_16x16x32_bf16 v[0:3], v[38:41], v[50:53], v[0:3]
	global_load_dwordx4 v[38:41], v[94:95], off offset:1280
	global_load_dwordx4 v[50:53], v[94:95], off offset:1344
	s_waitcnt vmcnt(14)
	v_mfma_f32_16x16x32_bf16 v[0:3], v[46:49], v[58:61], v[0:3]
	global_load_dwordx4 v[46:49], v[96:97], off offset:1280
	global_load_dwordx4 v[58:61], v[96:97], off offset:1344
	s_waitcnt vmcnt(14)
	v_mfma_f32_16x16x32_bf16 v[0:3], v[54:57], v[62:65], v[0:3]
	global_load_dwordx4 v[54:57], v[94:95], off offset:1408
	global_load_dwordx4 v[62:65], v[96:97], off offset:1408
	s_waitcnt vmcnt(14)
	v_mfma_f32_16x16x32_bf16 v[0:3], v[66:69], v[70:73], v[0:3]
	s_waitcnt vmcnt(11)
	v_mfma_f32_16x16x32_bf16 v[0:3], v[26:29], v[78:81], v[0:3]
	global_load_dwordx4 v[26:29], v[94:95], off offset:1472
	global_load_dwordx4 v[66:69], v[96:97], off offset:1472
	s_waitcnt vmcnt(12)
	v_mfma_f32_16x16x32_bf16 v[0:3], v[74:77], v[82:85], v[0:3]
	global_load_dwordx4 v[70:73], v[94:95], off offset:1536
	global_load_dwordx4 v[74:77], v[94:95], off offset:1600
	s_waitcnt vmcnt(11)
	v_mfma_f32_16x16x32_bf16 v[0:3], v[22:25], v[30:33], v[0:3]
	global_load_dwordx4 v[22:25], v[96:97], off offset:1536
	global_load_dwordx4 v[30:33], v[96:97], off offset:1600
	s_waitcnt vmcnt(12)
	v_mfma_f32_16x16x32_bf16 v[0:3], v[34:37], v[42:45], v[0:3]
	global_load_dwordx4 v[34:37], v[94:95], off offset:1664
	global_load_dwordx4 v[42:45], v[94:95], off offset:1728
	s_waitcnt vmcnt(11)
	v_mfma_f32_16x16x32_bf16 v[0:3], v[38:41], v[46:49], v[0:3]
	global_load_dwordx4 v[38:41], v[96:97], off offset:1664
	global_load_dwordx4 v[46:49], v[96:97], off offset:1728
	s_waitcnt vmcnt(12)
	v_mfma_f32_16x16x32_bf16 v[0:3], v[50:53], v[58:61], v[0:3]
	global_load_dwordx4 v[50:53], v[94:95], off offset:1792
	s_waitcnt vmcnt(11)
	v_mfma_f32_16x16x32_bf16 v[0:3], v[54:57], v[62:65], v[0:3]
	global_load_dwordx4 v[54:57], v[96:97], off offset:1792
	s_waitcnt vmcnt(10)
	v_mfma_f32_16x16x32_bf16 v[0:3], v[26:29], v[66:69], v[0:3]
	global_load_dwordx4 v[26:29], v[94:95], off offset:1856
	global_load_dwordx4 v[58:61], v[96:97], off offset:1856
	s_waitcnt vmcnt(9)
; __device__ __forceinline__ unsigned cvt_pk_bf16(float lo, float hi) { unsigned r; asm volatile("v_cvt_pk_bf16_f32 %0, %1, %2" : "=v"(r) : "v"(lo), "v"(hi)); return r; }
; #define LAS __attribute__((address_space(3)))
;     __device__ __forceinline__ void operator()(const f32x4 (&acc)[2], int srow, int cgp, int kq) const { one(acc[0], srow, 2 * cgp, kq); one(acc[1], srow, 2 * cgp + 1, kq); }
;     ...
;         if constexpr (KS == 2) {
;             LAS f32x4* xch = (LAS f32x4*)lds;
;             if (kh == 1) xch[rg * 64 + lane] = acc[0] + (f32x4){0.f, 0.f, 0.f, 0.f};
;             __syncthreads();
;             if (kh == 0) { acc[0] += xch[rg * 64 + lane]; E(acc, srow, cg, kq); }
;             __syncthreads();
;         } else E(acc, srow, cg, kq);
;     __device__ __forceinline__ void operator()(const f32x4 (&acc)[1], int srow, int cg, int kq) const {
;         bf16_t* xp = xb + (size_t)(TP + srow) * D + cg * 16 + 4 * kq;
;         const u32x2 w0 = *(const u32x2*)xp; f32x4 a;
;         a[0] = __uint_as_float(w0.x << 16); a[1] = __uint_as_float(w0.x & 0xffff0000u); a[2] = __uint_as_float(w0.y << 16); a[3] = __uint_as_float(w0.y & 0xffff0000u);
;         a += acc[0] * alpha;
;         u32x2 w; w.x = cvt_pk_bf16(a[0], a[1]); w.y = cvt_pk_bf16(a[2], a[3]);
;         *(u32x2*)xp = w;
;         float ss = (a[0] * a[0] + a[1] * a[1]) + (a[2] * a[2] + a[3] * a[3]);
;         ss += __shfl_xor(ss, 16); ss += __shfl_xor(ss, 32);
;         if (kq == 0) ssps[(size_t)srow * 64 + cg] = ss;
;     }
	v_mfma_f32_16x16x32_bf16 v[0:3], v[70:73], v[22:25], v[0:3]
	global_load_dwordx4 v[22:25], v[94:95], off offset:1920
	global_load_dwordx4 v[62:65], v[94:95], off offset:1984
	s_waitcnt vmcnt(10)
	v_mfma_f32_16x16x32_bf16 v[0:3], v[74:77], v[30:33], v[0:3]
	global_load_dwordx4 v[30:33], v[96:97], off offset:1920
	global_load_dwordx4 v[66:69], v[96:97], off offset:1984
	s_waitcnt vmcnt(9)
	v_mfma_f32_16x16x32_bf16 v[0:3], v[34:37], v[38:41], v[0:3]
	global_load_dwordx4 v[34:37], v[94:95], off offset:2048
	global_load_dwordx4 v[38:41], v[96:97], off offset:2048
	s_waitcnt vmcnt(10)
	v_mfma_f32_16x16x32_bf16 v[0:3], v[42:45], v[46:49], v[0:3]
	global_load_dwordx4 v[42:45], v[94:95], off offset:2112
	global_load_dwordx4 v[46:49], v[96:97], off offset:2112
	s_waitcnt vmcnt(10)
	v_mfma_f32_16x16x32_bf16 v[0:3], v[50:53], v[54:57], v[0:3]
	s_waitcnt vmcnt(8)
	v_mfma_f32_16x16x32_bf16 v[0:3], v[26:29], v[58:61], v[0:3]
	global_load_dwordx4 v[26:29], v[94:95], off offset:2176
	global_load_dwordx4 v[50:53], v[94:95], off offset:2240
	s_waitcnt vmcnt(7)
	v_mfma_f32_16x16x32_bf16 v[0:3], v[22:25], v[30:33], v[0:3]
	global_load_dwordx4 v[22:25], v[96:97], off offset:2176
	global_load_dwordx4 v[30:33], v[96:97], off offset:2240
	global_load_dwordx4 v[54:57], v[94:95], off offset:2304
	global_load_dwordx4 v[58:61], v[94:95], off offset:2368
	s_waitcnt vmcnt(10)
	v_mfma_f32_16x16x32_bf16 v[0:3], v[62:65], v[66:69], v[0:3]
	s_waitcnt vmcnt(8)
	v_mfma_f32_16x16x32_bf16 v[0:3], v[34:37], v[38:41], v[0:3]
	global_load_dwordx4 v[34:37], v[96:97], off offset:2304
	global_load_dwordx4 v[38:41], v[96:97], off offset:2368
	s_waitcnt vmcnt(8)
	v_mfma_f32_16x16x32_bf16 v[0:3], v[42:45], v[46:49], v[0:3]
	s_waitcnt vmcnt(5)
	v_mfma_f32_16x16x32_bf16 v[0:3], v[26:29], v[22:25], v[0:3]
	global_load_dwordx4 v[22:25], v[94:95], off offset:2432
	global_load_dwordx4 v[26:29], v[94:95], off offset:2496
	s_waitcnt vmcnt(6)
	v_mfma_f32_16x16x32_bf16 v[0:3], v[50:53], v[30:33], v[0:3]
	global_load_dwordx4 v[30:33], v[96:97], off offset:2432
	global_load_dwordx4 v[42:45], v[96:97], off offset:2496
	s_waitcnt vmcnt(5)
	v_mfma_f32_16x16x32_bf16 v[0:3], v[54:57], v[34:37], v[0:3]
	global_load_dwordx4 v[34:37], v[94:95], off offset:2560
	s_waitcnt vmcnt(5)
	v_mfma_f32_16x16x32_bf16 v[0:3], v[58:61], v[38:41], v[0:3]
	global_load_dwordx4 v[38:41], v[96:97], off offset:2560
	s_waitcnt vmcnt(3)
	v_mfma_f32_16x16x32_bf16 v[0:3], v[22:25], v[30:33], v[0:3]
	global_load_dwordx4 v[22:25], v[94:95], off offset:2624
	global_load_dwordx4 v[30:33], v[96:97], off offset:2624
	s_waitcnt vmcnt(4)
	v_mfma_f32_16x16x32_bf16 v[0:3], v[26:29], v[42:45], v[0:3]
	global_load_dwordx4 v[26:29], v[94:95], off offset:2688
	s_waitcnt vmcnt(3)
	v_mfma_f32_16x16x32_bf16 v[0:3], v[34:37], v[38:41], v[0:3]
	global_load_dwordx4 v[34:37], v[96:97], off offset:2688
	s_waitcnt vmcnt(2)
	v_mfma_f32_16x16x32_bf16 v[0:3], v[22:25], v[30:33], v[0:3]
	global_load_dwordx4 v[22:25], v[94:95], off offset:2752
	s_waitcnt vmcnt(1)
	v_mfma_f32_16x16x32_bf16 v[0:3], v[26:29], v[34:37], v[0:3]
	global_load_dwordx4 v[26:29], v[96:97], off offset:2752
	s_waitcnt vmcnt(0)
	v_mfma_f32_16x16x32_bf16 v[0:3], v[22:25], v[26:29], v[0:3]
	s_and_saveexec_b64 s[14:15], s[2:3]
	s_nop 6
	v_pk_add_f32 v[24:25], v[2:3], 0 op_sel_hi:[1,0]
	v_pk_add_f32 v[22:23], v[0:1], 0 op_sel_hi:[1,0]
	ds_write_b128 v13, v[22:25]
	s_or_b64 exec, exec, s[14:15]
	s_waitcnt lgkmcnt(0)
	s_barrier
	s_and_saveexec_b64 s[14:15], s[4:5]
	s_cbranch_execz .LBB0_1381
	v_lshlrev_b32_e32 v4, 11, v20
	v_lshl_add_u64 v[22:23], s[42:43], 0, v[4:5]
	s_ashr_i32 s13, s12, 31
	v_lshl_add_u64 v[22:23], s[12:13], 1, v[22:23]
	v_mov_b32_e32 v11, v5
	v_lshl_add_u64 v[22:23], v[22:23], 0, v[10:11]
	v_add_co_u32_e32 v26, vcc, s21, v22
	s_nop 1
	v_addc_co_u32_e32 v27, vcc, 0, v23, vcc
	global_load_dwordx2 v[28:29], v[26:27], off
	ds_read_b128 v[22:25], v14
	v_cmp_lt_i32_e32 vcc, v17, v18
	s_waitcnt lgkmcnt(0)
	v_pk_add_f32 v[2:3], v[2:3], v[24:25]
	v_pk_add_f32 v[0:1], v[0:1], v[22:23]
	v_cndmask_b32_e32 v4, v16, v17, vcc
	v_lshlrev_b32_e32 v4, 2, v4
	v_cmp_lt_i32_e32 vcc, v19, v18
	s_waitcnt vmcnt(0)
	v_lshlrev_b32_e32 v22, 16, v28
	v_and_b32_e32 v23, 0xffff0000, v28
	v_lshlrev_b32_e32 v24, 16, v29
	v_and_b32_e32 v25, 0xffff0000, v29
	v_pk_fma_f32 v[2:3], v[2:3], 0.5, v[24:25] op_sel_hi:[1,0,1]
	v_pk_fma_f32 v[22:23], v[0:1], 0.5, v[22:23] op_sel_hi:[1,0,1]
	v_mul_f32_e32 v1, v3, v3
	v_mul_f32_e32 v0, v23, v23
	v_fmac_f32_e32 v0, v22, v22
	v_fmac_f32_e32 v1, v2, v2
	v_add_f32_e32 v0, v0, v1
	ds_bpermute_b32 v1, v4, v0
	v_cndmask_b32_e32 v4, v16, v19, vcc
	v_cvt_pk_bf16_f32 v22, v22, v23
	v_cvt_pk_bf16_f32 v23, v2, v3
	global_store_dwordx2 v[26:27], v[22:23], off
	s_waitcnt lgkmcnt(0)
	v_add_f32_e32 v0, v0, v1
	v_lshlrev_b32_e32 v1, 2, v4
	ds_bpermute_b32 v1, v1, v0
	s_and_b64 exec, exec, s[6:7]
	s_cbranch_execz .LBB0_1381
	v_lshlrev_b32_e32 v4, 8, v20
	v_lshl_add_u64 v[2:3], s[92:93], 0, v[4:5]
	s_ashr_i32 s1, s0, 31
	v_lshl_add_u64 v[2:3], s[0:1], 2, v[2:3]
	s_waitcnt lgkmcnt(0)
	v_add_f32_e32 v0, v0, v1
	global_store_dword v[2:3], v0, off
	s_branch .LBB0_1381
.LBB0_1387:
	s_cmpk_lt_i32 s18, 0x200
	s_movk_i32 s0, 0xb00
	s_cselect_b64 s[2:3], -1, 0
	s_cmpk_gt_i32 s18, 0x1ff
	v_readfirstlane_b32 s26, v254
	s_cbranch_scc1 .LBB0_1393
	s_sub_i32 s99, 0x1ff, s18
	s_ashr_i32 s1, s99, 31
	s_lshr_b32 s1, s1, 29
	s_add_i32 s1, s99, s1
	s_and_b32 s4, s1, -8
	s_sub_i32 s6, s99, s4
	s_cmp_gt_i32 s6, -1
	s_cbranch_scc0 .LBB0_1390
	s_lshl_b32 s7, s6, 6
	s_cbranch_execz .LBB0_1391
	s_branch .LBB0_1392

;     __host__ __device__ bool next(int i, Unit& u) const {
;         const long L = (long)i * G + c; if (L >= nwg) return false;
;         int wgid = (int)L; { const int q = nwg / NXCD, r = nwg % NXCD, xcd = wgid % NXCD, off = wgid / NXCD; wgid = (xcd < r ? xcd * (q + 1) : r * (q + 1) + (xcd - r) * q) + off; }
;         const int nig = WGM * nN, gid = wgid / nig, fm = gid * WGM, gsz = (nM - fm) < WGM ? (nM - fm) : WGM;
;         u.pm = fm + ((wgid % nig) % gsz); u.pn = (wgid % nig) / gsz; return true;
; template <class Epi, class Sched, bool ALIGN_EPI = false, bool SP2 = false>
; __device__ __forceinline__ void gemm_phase(PG8_LAS unsigned char* lds, const Gemm g, const Sched& S, const Epi& E) {
;     ...
;         const bool has_next = S.next(ui + 1, nxt);
;         const char* nA = has_next ? (const char*)g.A + (size_t)nxt.pm * tstep : cA; const char* nB = has_next ? (const char*)g.Bt + (size_t)nxt.pn * tstep : cB;
.LBB0_1399:
	v_lshl_add_u32 v252, s62, 8, v156
	v_lshl_or_b32 v253, s14, 8, v158
	v_lshlrev_b32_e32 v253, 1, v253
	v_lshl_add_u32 v252, v252, 11, v253
	global_load_dwordx4 v[230:233], v252, s[42:43]
	global_load_dwordx4 v[234:237], v252, s[42:43] offset:256
	v_add_u32_e32 v253, 0x8000, v252
	global_load_dwordx4 v[238:241], v253, s[42:43]
	global_load_dwordx4 v[242:245], v253, s[42:43] offset:256
	v_add_u32_e32 v253, 0x10000, v252
	global_load_dwordx4 v[246:249], v253, s[42:43]
	global_load_dwordx4 v[250:253], v253, s[42:43] offset:256
	s_add_i32 s59, s59, 1
	s_mul_i32 s0, s59, s50
	s_mul_hi_u32 s1, s59, s51
	s_add_i32 s1, s1, s0
	s_mul_i32 s0, s59, s51
	s_add_u32 s4, s0, s18
	s_addc_u32 s5, s1, s56
	v_cmp_gt_i64_e32 vcc, s[4:5], v[142:143]
	v_cmp_lt_i64_e64 s[0:1], s[4:5], v[140:141]
	s_cbranch_vccnz .LBB0_1405
	s_sub_i32 s4, 0x1ff, s4
	s_ashr_i32 s5, s4, 31
	s_lshr_b32 s5, s5, 29
	s_add_i32 s28, s4, s5
	s_and_b32 s5, s28, -8
	s_sub_i32 s29, s4, s5
	s_cmp_gt_i32 s29, -1
	s_mov_b64 s[4:5], -1
	s_cbranch_scc0 .LBB0_1402
	s_lshl_b32 s60, s29, 6
	s_mov_b64 s[4:5], 0

; __device__ __forceinline__ int opq_tid() { int t = threadIdx.x; asm volatile("" : "+v"(t)); return t; }
; __device__ __forceinline__ int opq_bid() { int b = blockIdx.x; asm volatile("" : "+s"(b)); return b; }
; #define SK_LOAD(AR, BR, k0) do { _Pragma("unroll") for (int i = 0; i < UNR; ++i) { AR[i] = *(const bf16x8*)(ap + (k0) + 32 * i); \
;             _Pragma("unroll") for (int g = 0; g < NG; ++g) BR[g][i] = *(const bf16x8*)(bp[g] + (k0) + 32 * i); } } while (0)
; #define SK_MMA(AR, BR) do { _Pragma("unroll") for (int i = 0; i < UNR; ++i) _Pragma("unroll") for (int g = 0; g < NG; ++g) acc[g] = __builtin_amdgcn_mfma_f32_16x16x32_bf16(BR[g][i], AR[i], acc[g], 0, 0, 0); } while (0)
;     const int tid = opq_tid(), lane = tid & 63, w = tid >> 6, rr = lane & 15, kq = lane >> 4;
;     const int rg = KS == 2 ? (w & 3) : w, kh = KS == 2 ? (w >> 2) : 0, KL = K / KS;
;     for (int u = (opq_bid() + (int)gridDim.x - bshift) % (int)gridDim.x; u < 2 * KS * ngroups; u += gridDim.x) {
;         const int hv = u & (2 * KS - 1), cg = u / (2 * KS), srow = hv * (128 / KS) + rg * 16 + rr;
;         const bf16_t* ap = A + (size_t)srow * K + kh * KL + 8 * kq;
;         const bf16_t* bp[NG]; f32x4 acc[NG];
; #pragma unroll
;         for (int g = 0; g < NG; ++g) { bp[g] = Bt + (size_t)(Epi::brow(cg, g) + rr) * K + kh * KL + 8 * kq; acc[g] = (f32x4){0.f, 0.f, 0.f, 0.f}; }
;         bf16x8 a0[UNR], a1[UNR], b0[NG][UNR], b1[NG][UNR];
;     ...
;         SK_LOAD(a0, b0, 0);
;         for (int k = 0; k < KL; k += 64 * UNR) {
;             SK_LOAD(a1, b1, k + 32 * UNR);
;             SK_MMA(a0, b0);
;             if (k + 64 * UNR < KL) SK_LOAD(a0, b0, k + 64 * UNR);
;             SK_MMA(a1, b1);
;         }
.LBB0_1572:
	s_ashr_i32 s0, s16, 31
	s_lshr_b32 s0, s0, 30
	s_add_i32 s0, s16, s0
	s_ashr_i32 s0, s0, 2
	s_lshl_b32 s12, s0, 4
	v_or_b32_e32 v0, s12, v12
	v_mad_i64_i32 v[94:95], s[14:15], v0, s20, v[8:9]
	global_load_dwordx4 v[0:3], v[94:95], off
	s_and_b32 s1, s17, 0xc0
	v_or_b32_e32 v20, s1, v15
	v_mul_u32_u24_e32 v4, 0xb00, v20
	v_lshlrev_b32_e32 v4, 1, v4
	s_waitcnt vmcnt(4)
	v_lshl_add_u64 v[96:97], v[6:7], 0, v[4:5]
	global_load_dwordx4 v[22:25], v[94:95], off offset:64
	global_load_dwordx4 v[26:29], v[96:97], off
	global_load_dwordx4 v[30:33], v[96:97], off offset:64
	global_load_dwordx4 v[34:37], v[94:95], off offset:128
	global_load_dwordx4 v[38:41], v[94:95], off offset:192
	global_load_dwordx4 v[42:45], v[96:97], off offset:128
	global_load_dwordx4 v[46:49], v[96:97], off offset:192
	global_load_dwordx4 v[50:53], v[94:95], off offset:256
	global_load_dwordx4 v[54:57], v[94:95], off offset:320
	global_load_dwordx4 v[58:61], v[96:97], off offset:256
	global_load_dwordx4 v[62:65], v[96:97], off offset:320
	global_load_dwordx4 v[66:69], v[94:95], off offset:384
	global_load_dwordx4 v[70:73], v[94:95], off offset:448
	global_load_dwordx4 v[74:77], v[96:97], off offset:384
	global_load_dwordx4 v[78:81], v[96:97], off offset:448
	global_load_dwordx4 v[82:85], v[94:95], off offset:512
	global_load_dwordx4 v[86:89], v[94:95], off offset:576
	s_waitcnt vmcnt(15)
	v_mfma_f32_16x16x32_bf16 v[0:3], v[0:3], v[26:29], 0
	global_load_dwordx4 v[26:29], v[96:97], off offset:512
	global_load_dwordx4 v[90:93], v[96:97], off offset:576
	s_waitcnt vmcnt(16)
	v_mfma_f32_16x16x32_bf16 v[0:3], v[22:25], v[30:33], v[0:3]
	global_load_dwordx4 v[22:25], v[94:95], off offset:640
	global_load_dwordx4 v[30:33], v[94:95], off offset:704
	s_waitcnt vmcnt(15)
	v_mfma_f32_16x16x32_bf16 v[0:3], v[34:37], v[42:45], v[0:3]
	global_load_dwordx4 v[34:37], v[96:97], off offset:640
	global_load_dwordx4 v[42:45], v[96:97], off offset:704
	s_waitcnt vmcnt(16)
	v_mfma_f32_16x16x32_bf16 v[0:3], v[38:41], v[46:49], v[0:3]
	global_load_dwordx4 v[38:41], v[94:95], off offset:768
	global_load_dwordx4 v[46:49], v[94:95], off offset:832
	s_waitcnt vmcnt(15)
	v_mfma_f32_16x16x32_bf16 v[0:3], v[50:53], v[58:61], v[0:3]
	global_load_dwordx4 v[50:53], v[96:97], off offset:768
	global_load_dwordx4 v[58:61], v[96:97], off offset:832
	s_waitcnt vmcnt(16)
	v_mfma_f32_16x16x32_bf16 v[0:3], v[54:57], v[62:65], v[0:3]
	global_load_dwordx4 v[54:57], v[94:95], off offset:896
	global_load_dwordx4 v[62:65], v[96:97], off offset:896
	s_waitcnt vmcnt(15)
	v_mfma_f32_16x16x32_bf16 v[0:3], v[66:69], v[74:77], v[0:3]
	global_load_dwordx4 v[66:69], v[94:95], off offset:960
	s_waitcnt vmcnt(15)
	v_mfma_f32_16x16x32_bf16 v[0:3], v[70:73], v[78:81], v[0:3]
	global_load_dwordx4 v[70:73], v[96:97], off offset:960
	s_waitcnt vmcnt(13)
	v_mfma_f32_16x16x32_bf16 v[0:3], v[82:85], v[26:29], v[0:3]
	global_load_dwordx4 v[26:29], v[94:95], off offset:1024
	global_load_dwordx4 v[74:77], v[94:95], off offset:1088
	global_load_dwordx4 v[78:81], v[96:97], off offset:1024
	global_load_dwordx4 v[82:85], v[96:97], off offset:1088
	s_waitcnt vmcnt(16)
	v_mfma_f32_16x16x32_bf16 v[0:3], v[86:89], v[90:93], v[0:3]
	s_waitcnt vmcnt(13)
	v_mfma_f32_16x16x32_bf16 v[0:3], v[22:25], v[34:37], v[0:3]
	global_load_dwordx4 v[22:25], v[94:95], off offset:1152
	global_load_dwordx4 v[34:37], v[94:95], off offset:1216
	s_waitcnt vmcnt(14)
	v_mfma_f32_16x16x32_bf16 v[0:3], v[30:33], v[42:45], v[0:3]
	global_load_dwordx4 v[30:33], v[96:97], off offset:1152
	global_load_dwordx4 v[42:45], v[96:97], off offset:1216
	s_waitcnt vmcnt(13)
	v_mfma_f32_16x16x32_bf16 v[0:3], v[38:41], v[50:53], v[0:3]
	global_load_dwordx4 v[38:41], v[94:95], off offset:1280
	global_load_dwordx4 v[50:53], v[94:95], off offset:1344
	s_waitcnt vmcnt(14)
	v_mfma_f32_16x16x32_bf16 v[0:3], v[46:49], v[58:61], v[0:3]
	global_load_dwordx4 v[46:49], v[96:97], off offset:1280
	global_load_dwordx4 v[58:61], v[96:97], off offset:1344
	s_waitcnt vmcnt(14)
	v_mfma_f32_16x16x32_bf16 v[0:3], v[54:57], v[62:65], v[0:3]
	global_load_dwordx4 v[54:57], v[94:95], off offset:1408
	global_load_dwordx4 v[62:65], v[96:97], off offset:1408
	s_waitcnt vmcnt(14)
	v_mfma_f32_16x16x32_bf16 v[0:3], v[66:69], v[70:73], v[0:3]
	s_waitcnt vmcnt(11)
	v_mfma_f32_16x16x32_bf16 v[0:3], v[26:29], v[78:81], v[0:3]
	global_load_dwordx4 v[26:29], v[94:95], off offset:1472
	global_load_dwordx4 v[66:69], v[96:97], off offset:1472
	s_waitcnt vmcnt(12)
	v_mfma_f32_16x16x32_bf16 v[0:3], v[74:77], v[82:85], v[0:3]
	global_load_dwordx4 v[70:73], v[94:95], off offset:1536
	global_load_dwordx4 v[74:77], v[94:95], off offset:1600
	s_waitcnt vmcnt(11)
	v_mfma_f32_16x16x32_bf16 v[0:3], v[22:25], v[30:33], v[0:3]
	global_load_dwordx4 v[22:25], v[96:97], off offset:1536
	global_load_dwordx4 v[30:33], v[96:97], off offset:1600
	s_waitcnt vmcnt(12)
	v_mfma_f32_16x16x32_bf16 v[0:3], v[34:37], v[42:45], v[0:3]
	global_load_dwordx4 v[34:37], v[94:95], off offset:1664
	global_load_dwordx4 v[42:45], v[94:95], off offset:1728
	s_waitcnt vmcnt(11)
	v_mfma_f32_16x16x32_bf16 v[0:3], v[38:41], v[46:49], v[0:3]
	global_load_dwordx4 v[38:41], v[96:97], off offset:1664
	global_load_dwordx4 v[46:49], v[96:97], off offset:1728
	s_waitcnt vmcnt(12)
	v_mfma_f32_16x16x32_bf16 v[0:3], v[50:53], v[58:61], v[0:3]
	global_load_dwordx4 v[50:53], v[94:95], off offset:1792
	s_waitcnt vmcnt(11)
	v_mfma_f32_16x16x32_bf16 v[0:3], v[54:57], v[62:65], v[0:3]
	global_load_dwordx4 v[54:57], v[96:97], off offset:1792
	s_waitcnt vmcnt(10)
	v_mfma_f32_16x16x32_bf16 v[0:3], v[26:29], v[66:69], v[0:3]
	global_load_dwordx4 v[26:29], v[94:95], off offset:1856
	global_load_dwordx4 v[58:61], v[96:97], off offset:1856
	s_waitcnt vmcnt(9)
; __device__ __forceinline__ unsigned cvt_pk_bf16(float lo, float hi) { unsigned r; asm volatile("v_cvt_pk_bf16_f32 %0, %1, %2" : "=v"(r) : "v"(lo), "v"(hi)); return r; }
; #define LAS __attribute__((address_space(3)))
;     __device__ __forceinline__ void operator()(const f32x4 (&acc)[2], int srow, int cgp, int kq) const { one(acc[0], srow, 2 * cgp, kq); one(acc[1], srow, 2 * cgp + 1, kq); }
;     ...
;         if constexpr (KS == 2) {
;             LAS f32x4* xch = (LAS f32x4*)lds;
;             if (kh == 1) xch[rg * 64 + lane] = acc[0] + (f32x4){0.f, 0.f, 0.f, 0.f};
;             __syncthreads();
;             if (kh == 0) { acc[0] += xch[rg * 64 + lane]; E(acc, srow, cg, kq); }
;             __syncthreads();
;         } else E(acc, srow, cg, kq);
;     __device__ __forceinline__ void operator()(const f32x4 (&acc)[1], int srow, int cg, int kq) const {
;         bf16_t* xp = xb + (size_t)(TP + srow) * D + cg * 16 + 4 * kq;
;         const u32x2 w0 = *(const u32x2*)xp; f32x4 a;
;         a[0] = __uint_as_float(w0.x << 16); a[1] = __uint_as_float(w0.x & 0xffff0000u); a[2] = __uint_as_float(w0.y << 16); a[3] = __uint_as_float(w0.y & 0xffff0000u);
;         a += acc[0] * alpha;
;         u32x2 w; w.x = cvt_pk_bf16(a[0], a[1]); w.y = cvt_pk_bf16(a[2], a[3]);
;         *(u32x2*)xp = w;
;         float ss = (a[0] * a[0] + a[1] * a[1]) + (a[2] * a[2] + a[3] * a[3]);
;         ss += __shfl_xor(ss, 16); ss += __shfl_xor(ss, 32);
;         if (kq == 0) ssps[(size_t)srow * 64 + cg] = ss;
;     }
	v_mfma_f32_16x16x32_bf16 v[0:3], v[70:73], v[22:25], v[0:3]
	global_load_dwordx4 v[22:25], v[94:95], off offset:1920
	global_load_dwordx4 v[62:65], v[94:95], off offset:1984
	s_waitcnt vmcnt(10)
	v_mfma_f32_16x16x32_bf16 v[0:3], v[74:77], v[30:33], v[0:3]
	global_load_dwordx4 v[30:33], v[96:97], off offset:1920
	global_load_dwordx4 v[66:69], v[96:97], off offset:1984
	s_waitcnt vmcnt(9)
	v_mfma_f32_16x16x32_bf16 v[0:3], v[34:37], v[38:41], v[0:3]
	global_load_dwordx4 v[34:37], v[94:95], off offset:2048
	global_load_dwordx4 v[38:41], v[96:97], off offset:2048
	s_waitcnt vmcnt(10)
	v_mfma_f32_16x16x32_bf16 v[0:3], v[42:45], v[46:49], v[0:3]
	global_load_dwordx4 v[42:45], v[94:95], off offset:2112
	global_load_dwordx4 v[46:49], v[96:97], off offset:2112
	s_waitcnt vmcnt(10)
	v_mfma_f32_16x16x32_bf16 v[0:3], v[50:53], v[54:57], v[0:3]
	s_waitcnt vmcnt(8)
	v_mfma_f32_16x16x32_bf16 v[0:3], v[26:29], v[58:61], v[0:3]
	global_load_dwordx4 v[26:29], v[94:95], off offset:2176
	global_load_dwordx4 v[50:53], v[94:95], off offset:2240
	s_waitcnt vmcnt(7)
	v_mfma_f32_16x16x32_bf16 v[0:3], v[22:25], v[30:33], v[0:3]
	global_load_dwordx4 v[22:25], v[96:97], off offset:2176
	global_load_dwordx4 v[30:33], v[96:97], off offset:2240
	global_load_dwordx4 v[54:57], v[94:95], off offset:2304
	global_load_dwordx4 v[58:61], v[94:95], off offset:2368
	s_waitcnt vmcnt(10)
	v_mfma_f32_16x16x32_bf16 v[0:3], v[62:65], v[66:69], v[0:3]
	s_waitcnt vmcnt(8)
	v_mfma_f32_16x16x32_bf16 v[0:3], v[34:37], v[38:41], v[0:3]
	global_load_dwordx4 v[34:37], v[96:97], off offset:2304
	global_load_dwordx4 v[38:41], v[96:97], off offset:2368
	s_waitcnt vmcnt(8)
	v_mfma_f32_16x16x32_bf16 v[0:3], v[42:45], v[46:49], v[0:3]
	s_waitcnt vmcnt(5)
	v_mfma_f32_16x16x32_bf16 v[0:3], v[26:29], v[22:25], v[0:3]
	global_load_dwordx4 v[22:25], v[94:95], off offset:2432
	global_load_dwordx4 v[26:29], v[94:95], off offset:2496
	s_waitcnt vmcnt(6)
	v_mfma_f32_16x16x32_bf16 v[0:3], v[50:53], v[30:33], v[0:3]
	global_load_dwordx4 v[30:33], v[96:97], off offset:2432
	global_load_dwordx4 v[42:45], v[96:97], off offset:2496
	s_waitcnt vmcnt(5)
	v_mfma_f32_16x16x32_bf16 v[0:3], v[54:57], v[34:37], v[0:3]
	global_load_dwordx4 v[34:37], v[94:95], off offset:2560
	s_waitcnt vmcnt(5)
	v_mfma_f32_16x16x32_bf16 v[0:3], v[58:61], v[38:41], v[0:3]
	global_load_dwordx4 v[38:41], v[96:97], off offset:2560
	s_waitcnt vmcnt(3)
	v_mfma_f32_16x16x32_bf16 v[0:3], v[22:25], v[30:33], v[0:3]
	global_load_dwordx4 v[22:25], v[94:95], off offset:2624
	global_load_dwordx4 v[30:33], v[96:97], off offset:2624
	s_waitcnt vmcnt(4)
	v_mfma_f32_16x16x32_bf16 v[0:3], v[26:29], v[42:45], v[0:3]
	global_load_dwordx4 v[26:29], v[94:95], off offset:2688
	s_waitcnt vmcnt(3)
	v_mfma_f32_16x16x32_bf16 v[0:3], v[34:37], v[38:41], v[0:3]
	global_load_dwordx4 v[34:37], v[96:97], off offset:2688
	s_waitcnt vmcnt(2)
	v_mfma_f32_16x16x32_bf16 v[0:3], v[22:25], v[30:33], v[0:3]
	global_load_dwordx4 v[22:25], v[94:95], off offset:2752
	s_waitcnt vmcnt(1)
	v_mfma_f32_16x16x32_bf16 v[0:3], v[26:29], v[34:37], v[0:3]
	global_load_dwordx4 v[26:29], v[96:97], off offset:2752
	s_waitcnt vmcnt(0)
	v_mfma_f32_16x16x32_bf16 v[0:3], v[22:25], v[26:29], v[0:3]
	s_and_saveexec_b64 s[14:15], s[2:3]
	s_nop 6
	v_pk_add_f32 v[24:25], v[2:3], 0 op_sel_hi:[1,0]
	v_pk_add_f32 v[22:23], v[0:1], 0 op_sel_hi:[1,0]
	ds_write_b128 v13, v[22:25]
	s_or_b64 exec, exec, s[14:15]
	s_waitcnt lgkmcnt(0)
	s_barrier
	s_and_saveexec_b64 s[14:15], s[4:5]
	s_cbranch_execz .LBB0_1571
	v_lshlrev_b32_e32 v4, 11, v20
	v_lshl_add_u64 v[22:23], s[42:43], 0, v[4:5]
	s_ashr_i32 s13, s12, 31
	v_lshl_add_u64 v[22:23], s[12:13], 1, v[22:23]
	v_mov_b32_e32 v11, v5
	v_lshl_add_u64 v[22:23], v[22:23], 0, v[10:11]
	v_add_co_u32_e32 v26, vcc, s21, v22
	s_nop 1
	v_addc_co_u32_e32 v27, vcc, 0, v23, vcc
	global_load_dwordx2 v[28:29], v[26:27], off
	ds_read_b128 v[22:25], v14
	v_cmp_lt_i32_e32 vcc, v17, v18
	s_waitcnt lgkmcnt(0)
	v_pk_add_f32 v[2:3], v[2:3], v[24:25]
	v_pk_add_f32 v[0:1], v[0:1], v[22:23]
	v_cndmask_b32_e32 v4, v16, v17, vcc
	v_lshlrev_b32_e32 v4, 2, v4
	v_cmp_lt_i32_e32 vcc, v19, v18
	s_waitcnt vmcnt(0)
	v_lshlrev_b32_e32 v22, 16, v28
	v_and_b32_e32 v23, 0xffff0000, v28
	v_lshlrev_b32_e32 v24, 16, v29
	v_and_b32_e32 v25, 0xffff0000, v29
	v_pk_fma_f32 v[2:3], v[2:3], 0.5, v[24:25] op_sel_hi:[1,0,1]
	v_pk_fma_f32 v[22:23], v[0:1], 0.5, v[22:23] op_sel_hi:[1,0,1]
	v_mul_f32_e32 v1, v3, v3
	v_mul_f32_e32 v0, v23, v23
	v_fmac_f32_e32 v0, v22, v22
	v_fmac_f32_e32 v1, v2, v2
	v_add_f32_e32 v0, v0, v1
	ds_bpermute_b32 v1, v4, v0
	v_cndmask_b32_e32 v4, v16, v19, vcc
	v_cvt_pk_bf16_f32 v22, v22, v23
	v_cvt_pk_bf16_f32 v23, v2, v3
	global_store_dwordx2 v[26:27], v[22:23], off
	s_waitcnt lgkmcnt(0)
	v_add_f32_e32 v0, v0, v1
	v_lshlrev_b32_e32 v1, 2, v4
	ds_bpermute_b32 v1, v1, v0
	s_and_b64 exec, exec, s[6:7]
	s_cbranch_execz .LBB0_1571
	v_lshlrev_b32_e32 v4, 8, v20
	v_lshl_add_u64 v[2:3], s[92:93], 0, v[4:5]
	s_ashr_i32 s1, s0, 31
	v_lshl_add_u64 v[2:3], s[0:1], 2, v[2:3]
	s_waitcnt lgkmcnt(0)
	v_add_f32_e32 v0, v0, v1
	global_store_dword v[2:3], v0, off
	s_branch .LBB0_1571
.LBB0_1577:
	s_cmpk_lt_i32 s18, 0x200
	s_movk_i32 s0, 0xb00
	s_cselect_b64 s[2:3], -1, 0
	s_cmpk_gt_i32 s18, 0x1ff
	v_readfirstlane_b32 s26, v254
	s_cbranch_scc1 .LBB0_1583
	s_sub_i32 s99, 0x1ff, s18
	s_ashr_i32 s1, s99, 31
	s_lshr_b32 s1, s1, 29
	s_add_i32 s1, s99, s1
	s_and_b32 s4, s1, -8
	s_sub_i32 s6, s99, s4
	s_cmp_gt_i32 s6, -1
	s_cbranch_scc0 .LBB0_1580
	s_lshl_b32 s7, s6, 6
	s_cbranch_execz .LBB0_1581
	s_branch .LBB0_1582

;     __host__ __device__ bool next(int i, Unit& u) const {
;         const long L = (long)i * G + c; if (L >= nwg) return false;
;         int wgid = (int)L; { const int q = nwg / NXCD, r = nwg % NXCD, xcd = wgid % NXCD, off = wgid / NXCD; wgid = (xcd < r ? xcd * (q + 1) : r * (q + 1) + (xcd - r) * q) + off; }
;         const int nig = WGM * nN, gid = wgid / nig, fm = gid * WGM, gsz = (nM - fm) < WGM ? (nM - fm) : WGM;
;         u.pm = fm + ((wgid % nig) % gsz); u.pn = (wgid % nig) / gsz; return true;
; template <class Epi, class Sched, bool ALIGN_EPI = false, bool SP2 = false>
; __device__ __forceinline__ void gemm_phase(PG8_LAS unsigned char* lds, const Gemm g, const Sched& S, const Epi& E) {
;     ...
;     if (!S.next(0, cur)) return;
.LBB0_2551:
	s_cmpk_lt_i32 s18, 0x200
	s_movk_i32 s0, 0xb00
	s_cselect_b64 s[2:3], -1, 0
	s_cmpk_gt_i32 s18, 0x1ff
	v_readfirstlane_b32 s26, v254
	s_cbranch_scc1 .LBB0_2557
	s_sub_i32 s99, 0x1ff, s18
	s_ashr_i32 s1, s99, 31
	s_lshr_b32 s1, s1, 29
	s_add_i32 s7, s99, s1
	s_and_b32 s1, s7, -8
	s_sub_i32 s1, s99, s1
	s_cmp_gt_i32 s1, -1
	s_cbranch_scc0 .LBB0_2554
	s_lshl_b32 s6, s1, 6
	s_ashr_i32 s4, s7, 3
	s_cbranch_execz .LBB0_2555
	s_branch .LBB0_2556

;     __host__ __device__ bool next(int i, Unit& u) const {
;         const long L = (long)i * G + c; if (L >= nwg) return false;
;         int wgid = (int)L; { const int q = nwg / NXCD, r = nwg % NXCD, xcd = wgid % NXCD, off = wgid / NXCD; wgid = (xcd < r ? xcd * (q + 1) : r * (q + 1) + (xcd - r) * q) + off; }
;         const int nig = WGM * nN, gid = wgid / nig, fm = gid * WGM, gsz = (nM - fm) < WGM ? (nM - fm) : WGM;
;         u.pm = fm + ((wgid % nig) % gsz); u.pn = (wgid % nig) / gsz; return true;
; template <class Epi, class Sched, bool ALIGN_EPI = false, bool SP2 = false>
; __device__ __forceinline__ void gemm_phase(PG8_LAS unsigned char* lds, const Gemm g, const Sched& S, const Epi& E) {
;     ...
;         const bool has_next = S.next(ui + 1, nxt);
;         const char* nA = has_next ? (const char*)g.A + (size_t)nxt.pm * tstep : cA; const char* nB = has_next ? (const char*)g.Bt + (size_t)nxt.pn * tstep : cB;
.LBB0_2563:
	v_lshl_add_u32 v252, s60, 8, v156
	v_lshl_or_b32 v253, s14, 8, v158
	v_lshlrev_b32_e32 v253, 1, v253
	v_lshl_add_u32 v252, v252, 11, v253
	global_load_dwordx4 v[230:233], v252, s[42:43]
	global_load_dwordx4 v[234:237], v252, s[42:43] offset:256
	v_add_u32_e32 v253, 0x8000, v252
	global_load_dwordx4 v[238:241], v253, s[42:43]
	global_load_dwordx4 v[242:245], v253, s[42:43] offset:256
	v_add_u32_e32 v253, 0x10000, v252
	global_load_dwordx4 v[246:249], v253, s[42:43]
	global_load_dwordx4 v[250:253], v253, s[42:43] offset:256
	s_add_i32 s57, s57, 1
	s_mul_i32 s0, s57, s44
	s_mul_hi_u32 s1, s57, s45
	s_add_i32 s1, s1, s0
	s_mul_i32 s0, s57, s45
	s_add_u32 s4, s0, s18
	s_addc_u32 s5, s1, s50
	v_cmp_gt_i64_e32 vcc, s[4:5], v[142:143]
	v_cmp_lt_i64_e64 s[0:1], s[4:5], v[140:141]
	s_cbranch_vccnz .LBB0_2569
	s_sub_i32 s4, 0x1ff, s4
	s_ashr_i32 s5, s4, 31
	s_lshr_b32 s5, s5, 29
	s_add_i32 s28, s4, s5
	s_and_b32 s5, s28, -8
	s_sub_i32 s29, s4, s5
	s_cmp_gt_i32 s29, -1
	s_mov_b64 s[4:5], -1
	s_cbranch_scc0 .LBB0_2566
	s_lshl_b32 s58, s29, 6
	s_mov_b64 s[4:5], 0
